# v86 + SADDR-form LDS-DMA in the P4 K-loop as well (16 address VALU per iteration removed)
# baseline (speedup 1.0000x reference)
.LBB0_817:
	ds_read_b128 v[130:133], v223
	ds_read_b128 v[134:137], v223 offset:1024
	ds_read_b128 v[138:141], v223 offset:2048
	ds_read_b128 v[142:145], v223 offset:3072
	ds_read_b128 v[146:149], v224
	ds_read_b128 v[150:153], v224 offset:1024
	ds_read_b128 v[154:157], v224 offset:2048
	ds_read_b128 v[158:161], v224 offset:3072
	s_add_u32 s6, s4, 0xfff00080
	s_addc_u32 s7, s5, -1
	s_cmp_eq_u32 s14, 60
	s_cselect_b32 s9, s19, s7
	s_cselect_b32 s8, s18, s6
	s_cselect_b32 s7, s79, s1
	s_cselect_b32 s6, s78, s0
	s_add_i32 m0, s35, 0xc000
	ds_read_b128 v[174:177], v225
	ds_read_b128 v[178:181], v225 offset:1024
	ds_read_b128 v[182:185], v225 offset:2048
	ds_read_b128 v[186:189], v225 offset:3072
	ds_read_b128 v[190:193], v225 offset:4096
	ds_read_b128 v[202:205], v225 offset:5120
	ds_read_b128 v[206:209], v225 offset:6144
	ds_read_b128 v[210:213], v225 offset:7168
	global_load_lds_dwordx4 v170, s[4:5]
	s_add_i32 m0, s35, 0xe000
	s_nop 0
	global_load_lds_dwordx4 v172, s[4:5]
	s_waitcnt vmcnt(8)
	s_waitcnt lgkmcnt(0)
	s_barrier
	s_waitcnt lgkmcnt(0)
	v_mfma_f32_16x16x32_bf16 v[14:17], v[130:133], v[174:177], v[14:17]
	v_mfma_f32_16x16x32_bf16 v[14:17], v[134:137], v[178:181], v[14:17]
	v_mfma_f32_16x16x32_bf16 v[10:13], v[138:141], v[174:177], v[10:13]
	v_mfma_f32_16x16x32_bf16 v[10:13], v[142:145], v[178:181], v[10:13]
	v_mfma_f32_16x16x32_bf16 v[34:37], v[130:133], v[182:185], v[34:37]
	v_mfma_f32_16x16x32_bf16 v[34:37], v[134:137], v[186:189], v[34:37]
	v_mfma_f32_16x16x32_bf16 v[26:29], v[138:141], v[182:185], v[26:29]
	v_mfma_f32_16x16x32_bf16 v[26:29], v[142:145], v[186:189], v[26:29]
	v_mfma_f32_16x16x32_bf16 v[46:49], v[130:133], v[190:193], v[46:49]
	v_mfma_f32_16x16x32_bf16 v[46:49], v[134:137], v[202:205], v[46:49]
	v_mfma_f32_16x16x32_bf16 v[42:45], v[138:141], v[190:193], v[42:45]
	v_mfma_f32_16x16x32_bf16 v[42:45], v[142:145], v[202:205], v[42:45]
	v_mfma_f32_16x16x32_bf16 v[62:65], v[130:133], v[206:209], v[62:65]
	v_mfma_f32_16x16x32_bf16 v[62:65], v[134:137], v[210:213], v[62:65]
	v_mfma_f32_16x16x32_bf16 v[58:61], v[138:141], v[206:209], v[58:61]
	v_mfma_f32_16x16x32_bf16 v[58:61], v[142:145], v[210:213], v[58:61]
	v_mfma_f32_16x16x32_bf16 v[6:9], v[146:149], v[174:177], v[6:9]
	v_mfma_f32_16x16x32_bf16 v[6:9], v[150:153], v[178:181], v[6:9]
	v_mfma_f32_16x16x32_bf16 v[2:5], v[154:157], v[174:177], v[2:5]
	v_mfma_f32_16x16x32_bf16 v[2:5], v[158:161], v[178:181], v[2:5]
	v_mfma_f32_16x16x32_bf16 v[22:25], v[146:149], v[182:185], v[22:25]
	v_mfma_f32_16x16x32_bf16 v[22:25], v[150:153], v[186:189], v[22:25]
	v_mfma_f32_16x16x32_bf16 v[18:21], v[154:157], v[182:185], v[18:21]
	v_mfma_f32_16x16x32_bf16 v[18:21], v[158:161], v[186:189], v[18:21]
	v_mfma_f32_16x16x32_bf16 v[38:41], v[146:149], v[190:193], v[38:41]
	v_mfma_f32_16x16x32_bf16 v[38:41], v[150:153], v[202:205], v[38:41]
	v_mfma_f32_16x16x32_bf16 v[30:33], v[154:157], v[190:193], v[30:33]
	v_mfma_f32_16x16x32_bf16 v[30:33], v[158:161], v[202:205], v[30:33]
	v_mfma_f32_16x16x32_bf16 v[54:57], v[146:149], v[206:209], v[54:57]
	v_mfma_f32_16x16x32_bf16 v[54:57], v[150:153], v[210:213], v[54:57]
	v_mfma_f32_16x16x32_bf16 v[50:53], v[154:157], v[206:209], v[50:53]
	v_mfma_f32_16x16x32_bf16 v[50:53], v[158:161], v[210:213], v[50:53]
	s_barrier
	s_add_i32 s15, s17, s33
	s_add_u32 s98, s6, 0x80
	s_addc_u32 s99, s7, 0
	s_add_u32 s100, s8, 0x80
	s_addc_u32 s101, s9, 0
	s_mov_b32 m0, s15
	ds_read_b128 v[174:177], v225 offset:16384
	ds_read_b128 v[178:181], v225 offset:17408
	ds_read_b128 v[182:185], v225 offset:18432
	ds_read_b128 v[186:189], v225 offset:19456
	ds_read_b128 v[190:193], v225 offset:20480
	ds_read_b128 v[202:205], v225 offset:21504
	ds_read_b128 v[206:209], v225 offset:22528
	ds_read_b128 v[210:213], v225 offset:23552
	global_load_lds_dwordx4 v164, s[6:7]
	s_add_i32 m0, s15, 0x2000
	s_add_u32 s44, s6, 0x100000
	s_addc_u32 s45, s7, 0
	s_add_i32 s15, s55, s33
	global_load_lds_dwordx4 v168, s[6:7]
	s_mov_b32 m0, s15
	s_nop 0
	global_load_lds_dwordx4 v164, s[44:45]
	s_add_i32 m0, s15, 0x2000
	s_nop 0
	global_load_lds_dwordx4 v168, s[44:45]
	s_mov_b32 m0, s35
	s_nop 0
	global_load_lds_dwordx4 v162, s[8:9]
	s_mov_b32 m0, s80
	s_nop 0
	global_load_lds_dwordx4 v166, s[8:9]
	s_waitcnt vmcnt(8)
	s_waitcnt lgkmcnt(0)
	s_barrier
	s_waitcnt lgkmcnt(0)
	v_mfma_f32_16x16x32_bf16 v[78:81], v[130:133], v[174:177], v[78:81]
	v_mfma_f32_16x16x32_bf16 v[78:81], v[134:137], v[178:181], v[78:81]
	v_mfma_f32_16x16x32_bf16 v[74:77], v[138:141], v[174:177], v[74:77]
	v_mfma_f32_16x16x32_bf16 v[74:77], v[142:145], v[178:181], v[74:77]
	v_mfma_f32_16x16x32_bf16 v[94:97], v[130:133], v[182:185], v[94:97]
	v_mfma_f32_16x16x32_bf16 v[94:97], v[134:137], v[186:189], v[94:97]
	v_mfma_f32_16x16x32_bf16 v[90:93], v[138:141], v[182:185], v[90:93]
	v_mfma_f32_16x16x32_bf16 v[90:93], v[142:145], v[186:189], v[90:93]
	v_mfma_f32_16x16x32_bf16 v[110:113], v[130:133], v[190:193], v[110:113]
	v_mfma_f32_16x16x32_bf16 v[110:113], v[134:137], v[202:205], v[110:113]
	v_mfma_f32_16x16x32_bf16 v[106:109], v[138:141], v[190:193], v[106:109]
	v_mfma_f32_16x16x32_bf16 v[106:109], v[142:145], v[202:205], v[106:109]
	v_mfma_f32_16x16x32_bf16 v[118:121], v[130:133], v[206:209], v[118:121]
	v_mfma_f32_16x16x32_bf16 v[118:121], v[134:137], v[210:213], v[118:121]
	v_mfma_f32_16x16x32_bf16 v[114:117], v[138:141], v[206:209], v[114:117]
	v_mfma_f32_16x16x32_bf16 v[114:117], v[142:145], v[210:213], v[114:117]
	v_mfma_f32_16x16x32_bf16 v[70:73], v[146:149], v[174:177], v[70:73]
	v_mfma_f32_16x16x32_bf16 v[70:73], v[150:153], v[178:181], v[70:73]
	v_mfma_f32_16x16x32_bf16 v[66:69], v[154:157], v[174:177], v[66:69]
	v_mfma_f32_16x16x32_bf16 v[66:69], v[158:161], v[178:181], v[66:69]
	v_mfma_f32_16x16x32_bf16 v[86:89], v[146:149], v[182:185], v[86:89]
	v_mfma_f32_16x16x32_bf16 v[86:89], v[150:153], v[186:189], v[86:89]
	v_mfma_f32_16x16x32_bf16 v[82:85], v[154:157], v[182:185], v[82:85]
	v_mfma_f32_16x16x32_bf16 v[82:85], v[158:161], v[186:189], v[82:85]
	v_mfma_f32_16x16x32_bf16 v[102:105], v[146:149], v[190:193], v[102:105]
	v_mfma_f32_16x16x32_bf16 v[102:105], v[150:153], v[202:205], v[102:105]
	v_mfma_f32_16x16x32_bf16 v[98:101], v[154:157], v[190:193], v[98:101]
	v_mfma_f32_16x16x32_bf16 v[98:101], v[158:161], v[202:205], v[98:101]
	v_mfma_f32_16x16x32_bf16 v[122:125], v[146:149], v[206:209], v[122:125]
	v_mfma_f32_16x16x32_bf16 v[122:125], v[150:153], v[210:213], v[122:125]
	v_mfma_f32_16x16x32_bf16 v[126:129], v[154:157], v[206:209], v[126:129]
	v_mfma_f32_16x16x32_bf16 v[126:129], v[158:161], v[210:213], v[126:129]
	s_barrier
	s_add_i32 s56, 0, 0x18000
	s_add_i32 s57, 0, 0x1c000
	v_add_u32_e32 v142, s56, v222
	v_add_u32_e32 v158, s57, v222
	ds_read_b128 v[130:133], v142
	ds_read_b128 v[134:137], v142 offset:1024
	ds_read_b128 v[138:141], v142 offset:2048
	ds_read_b128 v[142:145], v142 offset:3072
	ds_read_b128 v[146:149], v158
	ds_read_b128 v[150:153], v158 offset:1024
	ds_read_b128 v[154:157], v158 offset:2048
	ds_read_b128 v[158:161], v158 offset:3072
	s_add_u32 s8, s8, 0x100000
	s_addc_u32 s9, s9, 0
	s_mov_b32 m0, s59
	ds_read_b128 v[174:177], v225 offset:32768
	ds_read_b128 v[178:181], v225 offset:33792
	ds_read_b128 v[182:185], v225 offset:34816
	ds_read_b128 v[186:189], v225 offset:35840
	ds_read_b128 v[190:193], v225 offset:36864
	ds_read_b128 v[202:205], v225 offset:37888
	ds_read_b128 v[206:209], v225 offset:38912
	ds_read_b128 v[210:213], v225 offset:39936
	global_load_lds_dwordx4 v162, s[8:9]
	s_mov_b32 m0, s60
	s_nop 0
	global_load_lds_dwordx4 v166, s[8:9]
	s_waitcnt vmcnt(8)
	s_waitcnt lgkmcnt(0)
	s_barrier
	s_waitcnt lgkmcnt(0)
	v_mfma_f32_16x16x32_bf16 v[14:17], v[130:133], v[174:177], v[14:17]
	v_mfma_f32_16x16x32_bf16 v[14:17], v[134:137], v[178:181], v[14:17]
	v_mfma_f32_16x16x32_bf16 v[10:13], v[138:141], v[174:177], v[10:13]
	v_mfma_f32_16x16x32_bf16 v[10:13], v[142:145], v[178:181], v[10:13]
	v_mfma_f32_16x16x32_bf16 v[34:37], v[130:133], v[182:185], v[34:37]
	v_mfma_f32_16x16x32_bf16 v[34:37], v[134:137], v[186:189], v[34:37]
	v_mfma_f32_16x16x32_bf16 v[26:29], v[138:141], v[182:185], v[26:29]
	v_mfma_f32_16x16x32_bf16 v[26:29], v[142:145], v[186:189], v[26:29]
	v_mfma_f32_16x16x32_bf16 v[46:49], v[130:133], v[190:193], v[46:49]
	v_mfma_f32_16x16x32_bf16 v[46:49], v[134:137], v[202:205], v[46:49]
	v_mfma_f32_16x16x32_bf16 v[42:45], v[138:141], v[190:193], v[42:45]
	v_mfma_f32_16x16x32_bf16 v[42:45], v[142:145], v[202:205], v[42:45]
	v_mfma_f32_16x16x32_bf16 v[62:65], v[130:133], v[206:209], v[62:65]
	v_mfma_f32_16x16x32_bf16 v[62:65], v[134:137], v[210:213], v[62:65]
	v_mfma_f32_16x16x32_bf16 v[58:61], v[138:141], v[206:209], v[58:61]
	v_mfma_f32_16x16x32_bf16 v[58:61], v[142:145], v[210:213], v[58:61]
	v_mfma_f32_16x16x32_bf16 v[6:9], v[146:149], v[174:177], v[6:9]
	v_mfma_f32_16x16x32_bf16 v[6:9], v[150:153], v[178:181], v[6:9]
	v_mfma_f32_16x16x32_bf16 v[2:5], v[154:157], v[174:177], v[2:5]
	v_mfma_f32_16x16x32_bf16 v[2:5], v[158:161], v[178:181], v[2:5]
	v_mfma_f32_16x16x32_bf16 v[22:25], v[146:149], v[182:185], v[22:25]
	v_mfma_f32_16x16x32_bf16 v[22:25], v[150:153], v[186:189], v[22:25]
	v_mfma_f32_16x16x32_bf16 v[18:21], v[154:157], v[182:185], v[18:21]
	v_mfma_f32_16x16x32_bf16 v[18:21], v[158:161], v[186:189], v[18:21]
	v_mfma_f32_16x16x32_bf16 v[38:41], v[146:149], v[190:193], v[38:41]
	v_mfma_f32_16x16x32_bf16 v[38:41], v[150:153], v[202:205], v[38:41]
	v_mfma_f32_16x16x32_bf16 v[30:33], v[154:157], v[190:193], v[30:33]
	v_mfma_f32_16x16x32_bf16 v[30:33], v[158:161], v[202:205], v[30:33]
	v_mfma_f32_16x16x32_bf16 v[54:57], v[146:149], v[206:209], v[54:57]
	v_mfma_f32_16x16x32_bf16 v[54:57], v[150:153], v[210:213], v[54:57]
	v_mfma_f32_16x16x32_bf16 v[50:53], v[154:157], v[206:209], v[50:53]
	v_mfma_f32_16x16x32_bf16 v[50:53], v[158:161], v[210:213], v[50:53]
	s_barrier
	s_add_i32 s8, s56, s33
	s_mov_b32 m0, s8
	ds_read_b128 v[174:177], v225 offset:49152
	ds_read_b128 v[178:181], v225 offset:50176
	ds_read_b128 v[182:185], v225 offset:51200
	ds_read_b128 v[186:189], v225 offset:52224
	ds_read_b128 v[190:193], v225 offset:53248
	ds_read_b128 v[202:205], v225 offset:54272
	ds_read_b128 v[206:209], v225 offset:55296
	ds_read_b128 v[210:213], v225 offset:56320
	global_load_lds_dwordx4 v164, s[98:99]
	s_add_i32 m0, s8, 0x2000
	s_add_u32 s6, s6, 0x100080
	s_addc_u32 s7, s7, 0
	s_add_i32 s8, s57, s33
	global_load_lds_dwordx4 v168, s[98:99]
	s_mov_b32 m0, s8
	s_nop 0
	global_load_lds_dwordx4 v164, s[6:7]
	s_add_i32 m0, s8, 0x2000
	s_nop 0
	global_load_lds_dwordx4 v168, s[6:7]
	s_mov_b32 m0, s65
	s_nop 0
	global_load_lds_dwordx4 v162, s[100:101]
	s_mov_b32 m0, s66
	s_nop 0
	global_load_lds_dwordx4 v166, s[100:101]
	s_waitcnt vmcnt(8)
	s_waitcnt lgkmcnt(0)
	s_barrier
	s_waitcnt lgkmcnt(0)
	v_mfma_f32_16x16x32_bf16 v[78:81], v[130:133], v[174:177], v[78:81]
	v_mfma_f32_16x16x32_bf16 v[78:81], v[134:137], v[178:181], v[78:81]
	v_mfma_f32_16x16x32_bf16 v[74:77], v[138:141], v[174:177], v[74:77]
	v_mfma_f32_16x16x32_bf16 v[74:77], v[142:145], v[178:181], v[74:77]
	v_mfma_f32_16x16x32_bf16 v[94:97], v[130:133], v[182:185], v[94:97]
	v_mfma_f32_16x16x32_bf16 v[94:97], v[134:137], v[186:189], v[94:97]
	v_mfma_f32_16x16x32_bf16 v[90:93], v[138:141], v[182:185], v[90:93]
	v_mfma_f32_16x16x32_bf16 v[90:93], v[142:145], v[186:189], v[90:93]
	v_mfma_f32_16x16x32_bf16 v[110:113], v[130:133], v[190:193], v[110:113]
	v_mfma_f32_16x16x32_bf16 v[110:113], v[134:137], v[202:205], v[110:113]
	v_mfma_f32_16x16x32_bf16 v[106:109], v[138:141], v[190:193], v[106:109]
	v_mfma_f32_16x16x32_bf16 v[106:109], v[142:145], v[202:205], v[106:109]
	v_mfma_f32_16x16x32_bf16 v[118:121], v[130:133], v[206:209], v[118:121]
	v_mfma_f32_16x16x32_bf16 v[118:121], v[134:137], v[210:213], v[118:121]
	v_mfma_f32_16x16x32_bf16 v[114:117], v[138:141], v[206:209], v[114:117]
	v_mfma_f32_16x16x32_bf16 v[114:117], v[142:145], v[210:213], v[114:117]
	v_mfma_f32_16x16x32_bf16 v[70:73], v[146:149], v[174:177], v[70:73]
	v_mfma_f32_16x16x32_bf16 v[70:73], v[150:153], v[178:181], v[70:73]
	v_mfma_f32_16x16x32_bf16 v[66:69], v[154:157], v[174:177], v[66:69]
	v_mfma_f32_16x16x32_bf16 v[66:69], v[158:161], v[178:181], v[66:69]
	v_mfma_f32_16x16x32_bf16 v[86:89], v[146:149], v[182:185], v[86:89]
	v_mfma_f32_16x16x32_bf16 v[86:89], v[150:153], v[186:189], v[86:89]
	v_mfma_f32_16x16x32_bf16 v[82:85], v[154:157], v[182:185], v[82:85]
	v_mfma_f32_16x16x32_bf16 v[82:85], v[158:161], v[186:189], v[82:85]
	v_mfma_f32_16x16x32_bf16 v[102:105], v[146:149], v[190:193], v[102:105]
	v_mfma_f32_16x16x32_bf16 v[102:105], v[150:153], v[202:205], v[102:105]
	v_mfma_f32_16x16x32_bf16 v[98:101], v[154:157], v[190:193], v[98:101]
	v_mfma_f32_16x16x32_bf16 v[98:101], v[158:161], v[202:205], v[98:101]
	v_mfma_f32_16x16x32_bf16 v[122:125], v[146:149], v[206:209], v[122:125]
	v_mfma_f32_16x16x32_bf16 v[122:125], v[150:153], v[210:213], v[122:125]
	v_mfma_f32_16x16x32_bf16 v[126:129], v[154:157], v[206:209], v[126:129]
	v_mfma_f32_16x16x32_bf16 v[126:129], v[158:161], v[210:213], v[126:129]
	s_barrier
	s_add_i32 s14, s14, 2
	s_add_u32 s4, s4, 0x100
	s_addc_u32 s5, s5, 0
	s_add_u32 s0, s0, 0x100
	s_addc_u32 s1, s1, 0
	s_cmp_gt_u32 s14, 61
	s_cbranch_scc0 .LBB0_817
	s_and_b64 vcc, exec, s[28:29]
	s_cbranch_vccz .LBB0_820
	s_barrier
